# v43 + attention: wave group B issues the first K-fragment reads of its next QK^T at the head of its softmax phase (tile already complete at the interval's opening barrier)
# speedup vs baseline: 1.0124x; 1.0016x over previous
; __device__ __forceinline__ void partialSM(f32x16& p0, f32x16& p1, float& m_reg, float& mn, float& alpha) {
;   constexpr float C = SCALE * 1.4426950408889634f;
;   float pmax = p0[0]; for (int r = 1; r < 16; ++r) pmax = fmaxf(pmax, p0[r]); for (int r = 0; r < 16; ++r) pmax = fmaxf(pmax, p1[r]);
;   { auto rr = __builtin_amdgcn_permlane32_swap(__float_as_uint(pmax), __float_as_uint(pmax), false, false);
;     pmax = fmaxf(__uint_as_float(rr[0]), __uint_as_float(rr[1])); }
;   if (__builtin_expect(__all(pmax - m_reg <= THR / SCALE), 1)) { mn = m_reg; alpha = 1.f; }
;   else { mn = fmaxf(m_reg, pmax); alpha = __builtin_amdgcn_exp2f((m_reg - mn) * C); m_reg = mn; }
;   float mnC = -mn * C;
;   for (int r = 0; r < 16; ++r) p0[r] = fmaf(p0[r], C, mnC); for (int r = 0; r < 16; ++r) p1[r] = fmaf(p1[r], C, mnC);
;   for (int r = 0; r < 16; ++r) p0[r] = __builtin_amdgcn_exp2f(p0[r]);
; }
; __device__ __forceinline__ void finishSM(f32x16& p0, f32x16& p1, float alpha, float& l_reg, bf16x8& pa0, bf16x8& pa1, bf16x8& pa2, bf16x8& pa3) {
;   for (int r = 0; r < 16; ++r) p1[r] = __builtin_amdgcn_exp2f(p1[r]);
;   float ps = 0; for (int r = 0; r < 16; ++r) ps += p0[r]; for (int r = 0; r < 16; ++r) ps += p1[r];
;   { auto rr = __builtin_amdgcn_permlane32_swap(__float_as_uint(ps), __float_as_uint(ps), false, false);
;     ps = __uint_as_float(rr[0]) + __uint_as_float(rr[1]); }
;   l_reg = l_reg * alpha + ps;
;     ...
;   PK4(p0, 0, pa0); PK4(p0, 8, pa1); PK4(p1, 0, pa2); PK4(p1, 8, pa3);
;     ...
; }
; __device__ __forceinline__ void qkt(f32x16& p0, f32x16& p1, const char* Kn, const char* Kp, const bf16x8* qr, int r32, int hi) {
;   p0 = f32x16{}; p1 = f32x16{};
; #pragma unroll
;   for (int d0 = 0; d0 < 8; ++d0) { int cb = (d0 * 16 + hi * 8) * 2;
;     bf16x8 b0 = *reinterpret_cast<const bf16x8*>(Kn + KSWZ(r32, cb));
;     bf16x8 b1 = *reinterpret_cast<const bf16x8*>(Kn + KSWZ(32 + r32, cb));
;     p0 = __builtin_amdgcn_mfma_f32_32x32x16_bf16(b0, qr[d0], p0, 0, 0, 0);
;     p1 = __builtin_amdgcn_mfma_f32_32x32x16_bf16(b1, qr[d0], p1, 0, 0, 0); }
; #pragma unroll
;   for (int d1 = 0; d1 < 4; ++d1) { int cb = (d1 * 16 + hi * 8) * 2;
;     bf16x8 b0 = *reinterpret_cast<const bf16x8*>(Kp + KPSWZ(r32, cb));
;     bf16x8 b1 = *reinterpret_cast<const bf16x8*>(Kp + KPSWZ(32 + r32, cb));
;     p0 = __builtin_amdgcn_mfma_f32_32x32x16_bf16(b0, qr[8 + d1], p0, 0, 0, 0);
.Lpp_loop:
	s_barrier
	ds_read_b128 v[192:195], v160 offset:16384
	ds_read_b128 v[196:199], v160 offset:24576
	ds_read_b128 v[200:203], v161 offset:16384
	ds_read_b128 v[204:207], v161 offset:24576
	ds_read_b128 v[208:211], v162 offset:16384
	ds_read_b128 v[212:215], v162 offset:24576
	ds_read_b128 v[216:219], v163 offset:16384
	ds_read_b128 v[220:223], v163 offset:24576
	v_max3_f32 v250, v80, v81, v82
	v_max3_f32 v250, v250, v83, v84
	v_max3_f32 v250, v250, v85, v86
	v_max3_f32 v250, v250, v87, v88
	v_max3_f32 v250, v250, v89, v90
	v_max3_f32 v250, v250, v91, v92
	v_max3_f32 v250, v250, v93, v94
	v_max3_f32 v250, v250, v95, v64
	v_max3_f32 v250, v250, v65, v66
	v_max3_f32 v250, v250, v67, v68
	v_max3_f32 v250, v250, v69, v70
	v_max3_f32 v250, v250, v71, v72
	v_max3_f32 v250, v250, v73, v74
	v_max3_f32 v250, v250, v75, v76
	v_max3_f32 v250, v250, v77, v78
	v_max3_f32 v250, v250, v79, v79
	v_cmp_lt_f32_e64 vcc, s64, |v250|
	s_waitcnt vmcnt(0)
	ds_write_b128 v246, v[232:235]
	ds_write_b128 v246, v[236:239] offset:8192
	ds_write_b128 v248, v[240:243]
	ds_write_b128 v244, v[224:227]
	ds_write_b128 v244, v[228:231] offset:8192
	global_load_dwordx4 v[232:235], v180, s[50:51]
	global_load_dwordx4 v[236:239], v180, s[52:53]
	global_load_dwordx4 v[224:227], v180, s[54:55] offset:256
	global_load_dwordx4 v[228:231], v180, s[56:57] offset:256
	global_load_dwordx4 v[240:243], v181, s[58:59]
	s_cmp_lg_u32 s62, 0
	s_cbranch_scc1 .Lpp_safe_Ba
	s_cbranch_vccnz .Lpp_sw_Ba
	v_exp_f32_e32 v80, v80
	v_exp_f32_e32 v81, v81
	v_exp_f32_e32 v82, v82
	v_exp_f32_e32 v83, v83
	v_exp_f32_e32 v84, v84
	v_exp_f32_e32 v85, v85
	v_exp_f32_e32 v86, v86
	v_exp_f32_e32 v87, v87
	v_exp_f32_e32 v88, v88
	v_exp_f32_e32 v89, v89
	v_exp_f32_e32 v90, v90
	v_exp_f32_e32 v91, v91
	v_exp_f32_e32 v92, v92
	v_exp_f32_e32 v93, v93
	v_exp_f32_e32 v94, v94
	v_exp_f32_e32 v95, v95
	v_exp_f32_e32 v64, v64
	v_exp_f32_e32 v65, v65
	v_exp_f32_e32 v66, v66
	v_exp_f32_e32 v67, v67
	v_exp_f32_e32 v68, v68
	v_exp_f32_e32 v69, v69
	v_exp_f32_e32 v70, v70
	v_exp_f32_e32 v71, v71
	v_exp_f32_e32 v72, v72
	v_exp_f32_e32 v73, v73
	v_exp_f32_e32 v74, v74
	v_exp_f32_e32 v75, v75
	v_exp_f32_e32 v76, v76
	v_exp_f32_e32 v77, v77
	v_exp_f32_e32 v78, v78
	v_exp_f32_e32 v79, v79
	v_add_f32_e32 v249, v80, v81
	v_add_f32_e32 v250, v82, v83
	v_add_f32_e32 v251, v84, v85
	v_add_f32_e32 v182, v86, v87
	v_add_f32_e32 v249, v88, v249
	v_add_f32_e32 v250, v89, v250
	v_add_f32_e32 v251, v90, v251
	v_add_f32_e32 v182, v91, v182
	v_add_f32_e32 v249, v92, v249
	v_add_f32_e32 v250, v93, v250
	v_add_f32_e32 v251, v94, v251
	v_add_f32_e32 v182, v95, v182
	v_add_f32_e32 v249, v64, v249
	v_add_f32_e32 v250, v65, v250
	v_add_f32_e32 v251, v66, v251
	v_add_f32_e32 v182, v67, v182
	v_add_f32_e32 v249, v68, v249
	v_add_f32_e32 v250, v69, v250
	v_add_f32_e32 v251, v70, v251
	v_add_f32_e32 v182, v71, v182
	v_add_f32_e32 v249, v72, v249
	v_add_f32_e32 v250, v73, v250
	v_add_f32_e32 v251, v74, v251
	v_add_f32_e32 v182, v75, v182
	v_add_f32_e32 v249, v76, v249
	v_add_f32_e32 v250, v77, v250
	v_add_f32_e32 v251, v78, v251
	v_add_f32_e32 v182, v79, v182
	v_add_f32_e32 v249, v249, v250
	v_add_f32_e32 v251, v251, v182
	v_add_f32_e32 v249, v249, v251
	v_add_f32_e32 v176, v176, v249
	v_cvt_pk_bf16_f32 v144, v80, v81
	v_cvt_pk_bf16_f32 v145, v82, v83
	v_cvt_pk_bf16_f32 v146, v84, v85
	v_cvt_pk_bf16_f32 v147, v86, v87
	v_cvt_pk_bf16_f32 v148, v88, v89
	v_cvt_pk_bf16_f32 v149, v90, v91
	v_cvt_pk_bf16_f32 v150, v92, v93
	v_cvt_pk_bf16_f32 v151, v94, v95
	v_cvt_pk_bf16_f32 v152, v64, v65
	v_cvt_pk_bf16_f32 v153, v66, v67
	v_cvt_pk_bf16_f32 v154, v68, v69
	v_cvt_pk_bf16_f32 v155, v70, v71
	v_cvt_pk_bf16_f32 v156, v72, v73
	v_cvt_pk_bf16_f32 v157, v74, v75
	v_cvt_pk_bf16_f32 v158, v76, v77
	v_cvt_pk_bf16_f32 v159, v78, v79
.Lpp_send_Ba:
	s_add_i32 s11, s11, 1
	s_waitcnt lgkmcnt(6)
	v_mfma_f32_32x32x16_bf16 v[80:95], v[192:195], v[136:139], 0
	v_mfma_f32_32x32x16_bf16 v[64:79], v[196:199], v[136:139], 0
	s_add_i32 s36, s35, 2
	s_min_u32 s36, s36, 67
	s_lshl_b32 s44, s36, 6
	ds_read_b128 v[192:195], v164 offset:16384
	ds_read_b128 v[196:199], v164 offset:24576
	s_waitcnt lgkmcnt(6)
	v_mfma_f32_32x32x16_bf16 v[80:95], v[200:203], v[132:135], v[80:95]
	v_mfma_f32_32x32x16_bf16 v[64:79], v[204:207], v[132:135], v[64:79]
	s_add_i32 s45, s31, s44
	s_add_i32 s46, s24, s44
	s_add_i32 s46, s46, 0xffffff00
	ds_read_b128 v[200:203], v165 offset:16384
	ds_read_b128 v[204:207], v165 offset:24576
	s_waitcnt lgkmcnt(6)
	v_mfma_f32_32x32x16_bf16 v[80:95], v[208:211], v[128:131], v[80:95]
	v_mfma_f32_32x32x16_bf16 v[64:79], v[212:215], v[128:131], v[64:79]
	s_cmp_lt_u32 s36, 4
	s_cselect_b32 s36, s45, s46
	s_add_i32 s37, s35, 1
	ds_read_b128 v[208:211], v166 offset:16384
	ds_read_b128 v[212:215], v166 offset:24576
	s_waitcnt lgkmcnt(6)
	v_mfma_f32_32x32x16_bf16 v[80:95], v[216:219], v[124:127], v[80:95]
	v_mfma_f32_32x32x16_bf16 v[64:79], v[220:223], v[124:127], v[64:79]
	s_min_u32 s37, s37, 67
	s_lshl_b32 s44, s37, 6
	s_add_i32 s45, s31, s44
	ds_read_b128 v[216:219], v167 offset:16384
	ds_read_b128 v[220:223], v167 offset:24576
	s_waitcnt lgkmcnt(6)
	v_mfma_f32_32x32x16_bf16 v[80:95], v[192:195], v[120:123], v[80:95]
	v_mfma_f32_32x32x16_bf16 v[64:79], v[196:199], v[120:123], v[64:79]
	s_add_i32 s46, s24, s44
	s_add_i32 s46, s46, 0xffffff00
	s_cmp_lt_u32 s37, 4
	ds_read_b128 v[192:195], v168 offset:8192
	ds_read_b128 v[196:199], v168 offset:12288
	s_waitcnt lgkmcnt(6)
	v_mfma_f32_32x32x16_bf16 v[80:95], v[200:203], v[140:143], v[80:95]
	v_mfma_f32_32x32x16_bf16 v[64:79], v[204:207], v[140:143], v[64:79]
	s_cselect_b32 s37, s45, s46
	s_add_i32 s35, s35, 1
	s_lshl_b32 s44, s36, 12
	ds_read_b128 v[200:203], v169 offset:8192
	ds_read_b128 v[204:207], v169 offset:12288
	s_waitcnt lgkmcnt(6)
; __device__ __forceinline__ void qkt(f32x16& p0, f32x16& p1, const char* Kn, const char* Kp, const bf16x8* qr, int r32, int hi) {
;   p0 = f32x16{}; p1 = f32x16{};
; #pragma unroll
;   for (int d0 = 0; d0 < 8; ++d0) { int cb = (d0 * 16 + hi * 8) * 2;
;     bf16x8 b0 = *reinterpret_cast<const bf16x8*>(Kn + KSWZ(r32, cb));
;     bf16x8 b1 = *reinterpret_cast<const bf16x8*>(Kn + KSWZ(32 + r32, cb));
;     p0 = __builtin_amdgcn_mfma_f32_32x32x16_bf16(b0, qr[d0], p0, 0, 0, 0);
;     p1 = __builtin_amdgcn_mfma_f32_32x32x16_bf16(b1, qr[d0], p1, 0, 0, 0); }
; #pragma unroll
;   for (int d1 = 0; d1 < 4; ++d1) { int cb = (d1 * 16 + hi * 8) * 2;
;     bf16x8 b0 = *reinterpret_cast<const bf16x8*>(Kp + KPSWZ(r32, cb));
;     bf16x8 b1 = *reinterpret_cast<const bf16x8*>(Kp + KPSWZ(32 + r32, cb));
;     p0 = __builtin_amdgcn_mfma_f32_32x32x16_bf16(b0, qr[8 + d1], p0, 0, 0, 0);
;     p1 = __builtin_amdgcn_mfma_f32_32x32x16_bf16(b1, qr[8 + d1], p1, 0, 0, 0); }
; }
; __device__ __forceinline__ int v_st(int k, int c) { const int kk = (k & ~0xC) | ((k & 4) << 1) | ((k & 8) >> 1); return ((kk >> 3) * 4 + (c >> 5)) * 512 + ((kk & 7) * 32 + (c & 31)) * 2; }
; __device__ __forceinline__ int v_rd_base(int lane) { return ((lane & 3) << 3) | (((lane >> 2) & 3) << 6) | (((lane >> 4) & 1) << 5) | (((lane >> 5) & 1) << 8); }
; template <int OFF> __device__ __forceinline__ s16x4 tr_read(int vb) {
;   s16x4 r; asm volatile("ds_read_b64_tr_b16 %0, %1 offset:%2" : "=&v"(r) : "v"(vb), "i"(OFF) : "memory"); return r;
; }
; template <int D0> __device__ __forceinline__ void pv_one(f32x16& od, int vb, bf16x8 pa0, bf16x8 pa1, bf16x8 pa2, bf16x8 pa3) {
;   const s16x4 l0 = tr_read<v_rd_off(D0, 0, 0)>(vb), h0 = tr_read<v_rd_off(D0, 0, 1)>(vb), l1 = tr_read<v_rd_off(D0, 1, 0)>(vb), h1 = tr_read<v_rd_off(D0, 1, 1)>(vb);
;   const s16x4 l2 = tr_read<v_rd_off(D0, 2, 0)>(vb), h2 = tr_read<v_rd_off(D0, 2, 1)>(vb), l3 = tr_read<v_rd_off(D0, 3, 0)>(vb), h3 = tr_read<v_rd_off(D0, 3, 1)>(vb);
;   asm volatile("s_waitcnt lgkmcnt(0)" ::: "memory"); SBAR();
;     ...
;   od = __builtin_amdgcn_mfma_f32_32x32x16_bf16(pa0, PK(l0, h0), od, 0, 0, 0);
;   od = __builtin_amdgcn_mfma_f32_32x32x16_bf16(pa1, PK(l1, h1), od, 0, 0, 0);
;   od = __builtin_amdgcn_mfma_f32_32x32x16_bf16(pa2, PK(l2, h2), od, 0, 0, 0);
;   od = __builtin_amdgcn_mfma_f32_32x32x16_bf16(pa3, PK(l3, h3), od, 0, 0, 0);
;     ...
; }
	v_mfma_f32_32x32x16_bf16 v[80:95], v[208:211], v[116:119], v[80:95]
	v_mfma_f32_32x32x16_bf16 v[64:79], v[212:215], v[116:119], v[64:79]
	s_add_u32 s50, s47, s44
	s_addc_u32 s51, s63, 0
	s_add_u32 s52, s50, 0x20000
	ds_read_b128 v[208:211], v170 offset:8192
	ds_read_b128 v[212:215], v170 offset:12288
	s_waitcnt lgkmcnt(6)
	v_mfma_f32_32x32x16_bf16 v[80:95], v[216:219], v[112:115], v[80:95]
	v_mfma_f32_32x32x16_bf16 v[64:79], v[220:223], v[112:115], v[64:79]
	s_addc_u32 s53, s51, 0
	s_lshl_b32 s44, s37, 12
	s_add_u32 s54, s47, s44
	ds_read_b128 v[216:219], v171 offset:8192
	ds_read_b128 v[220:223], v171 offset:12288
	s_waitcnt lgkmcnt(6)
	v_mfma_f32_32x32x16_bf16 v[80:95], v[192:195], v[108:111], v[80:95]
	v_mfma_f32_32x32x16_bf16 v[64:79], v[196:199], v[108:111], v[64:79]
	s_addc_u32 s55, s63, 0
	s_add_u32 s56, s54, 0x20000
	s_addc_u32 s57, s55, 0
	ds_read_b64_tr_b16 v[192:193], v174 offset:0
	ds_read_b64_tr_b16 v[194:195], v174 offset:2048
	ds_read_b64_tr_b16 v[196:197], v174 offset:4096
	ds_read_b64_tr_b16 v[198:199], v174 offset:6144
	s_waitcnt lgkmcnt(8)
	v_mfma_f32_32x32x16_bf16 v[80:95], v[200:203], v[104:107], v[80:95]
	v_mfma_f32_32x32x16_bf16 v[64:79], v[204:207], v[104:107], v[64:79]
	s_lshl_b32 s44, s36, 10
	s_add_u32 s58, s60, s44
	s_addc_u32 s59, s61, 0
	ds_read_b64_tr_b16 v[200:201], v174 offset:8192
	ds_read_b64_tr_b16 v[202:203], v174 offset:10240
	ds_read_b64_tr_b16 v[204:205], v174 offset:12288
	ds_read_b64_tr_b16 v[206:207], v174 offset:14336
	s_waitcnt lgkmcnt(10)
	v_mfma_f32_32x32x16_bf16 v[80:95], v[208:211], v[100:103], v[80:95]
	v_mfma_f32_32x32x16_bf16 v[64:79], v[212:215], v[100:103], v[64:79]
	ds_read_b64_tr_b16 v[208:209], v174 offset:512
	ds_read_b64_tr_b16 v[210:211], v174 offset:2560
	ds_read_b64_tr_b16 v[212:213], v174 offset:4608
	ds_read_b64_tr_b16 v[214:215], v174 offset:6656
	s_waitcnt lgkmcnt(12)
	v_mfma_f32_32x32x16_bf16 v[80:95], v[216:219], v[96:99], v[80:95]
	v_mfma_f32_32x32x16_bf16 v[64:79], v[220:223], v[96:99], v[64:79]
	ds_read_b64_tr_b16 v[216:217], v174 offset:8704
	ds_read_b64_tr_b16 v[218:219], v174 offset:10752
	ds_read_b64_tr_b16 v[220:221], v174 offset:12800
	ds_read_b64_tr_b16 v[222:223], v174 offset:14848
	s_waitcnt lgkmcnt(12)
	v_mfma_f32_32x32x16_bf16 v[0:15], v[144:147], v[192:195], v[0:15]
	ds_read_b64_tr_b16 v[192:193], v174 offset:1024
	ds_read_b64_tr_b16 v[194:195], v174 offset:3072
	v_mfma_f32_32x32x16_bf16 v[0:15], v[148:151], v[196:199], v[0:15]
	ds_read_b64_tr_b16 v[196:197], v174 offset:5120
	ds_read_b64_tr_b16 v[198:199], v174 offset:7168
	s_waitcnt lgkmcnt(12)
	v_mfma_f32_32x32x16_bf16 v[0:15], v[152:155], v[200:203], v[0:15]
	ds_read_b64_tr_b16 v[200:201], v174 offset:9216
	ds_read_b64_tr_b16 v[202:203], v174 offset:11264
	v_mfma_f32_32x32x16_bf16 v[0:15], v[156:159], v[204:207], v[0:15]
	ds_read_b64_tr_b16 v[204:205], v174 offset:13312
	ds_read_b64_tr_b16 v[206:207], v174 offset:15360
	s_waitcnt lgkmcnt(12)
	v_mfma_f32_32x32x16_bf16 v[48:63], v[144:147], v[208:211], v[48:63]
	ds_read_b64_tr_b16 v[208:209], v174 offset:1536
	ds_read_b64_tr_b16 v[210:211], v174 offset:3584
	v_mfma_f32_32x32x16_bf16 v[48:63], v[148:151], v[212:215], v[48:63]
	ds_read_b64_tr_b16 v[212:213], v174 offset:5632
	ds_read_b64_tr_b16 v[214:215], v174 offset:7680
	s_waitcnt lgkmcnt(12)
	v_mfma_f32_32x32x16_bf16 v[48:63], v[152:155], v[216:219], v[48:63]
	ds_read_b64_tr_b16 v[216:217], v174 offset:9728
	ds_read_b64_tr_b16 v[218:219], v174 offset:11776
	v_mfma_f32_32x32x16_bf16 v[48:63], v[156:159], v[220:223], v[48:63]
	ds_read_b64_tr_b16 v[220:221], v174 offset:13824
	ds_read_b64_tr_b16 v[222:223], v174 offset:15872
	s_waitcnt lgkmcnt(12)
	v_mfma_f32_32x32x16_bf16 v[32:47], v[144:147], v[192:195], v[32:47]
	v_mfma_f32_32x32x16_bf16 v[32:47], v[148:151], v[196:199], v[32:47]
	s_waitcnt lgkmcnt(8)
	v_mfma_f32_32x32x16_bf16 v[32:47], v[152:155], v[200:203], v[32:47]
	v_mfma_f32_32x32x16_bf16 v[32:47], v[156:159], v[204:207], v[32:47]
	s_waitcnt lgkmcnt(4)
	v_mfma_f32_32x32x16_bf16 v[16:31], v[144:147], v[208:211], v[16:31]
	v_mfma_f32_32x32x16_bf16 v[16:31], v[148:151], v[212:215], v[16:31]
	s_waitcnt lgkmcnt(0)
	v_mfma_f32_32x32x16_bf16 v[16:31], v[152:155], v[216:219], v[16:31]
	v_mfma_f32_32x32x16_bf16 v[16:31], v[156:159], v[220:223], v[16:31]
	s_barrier
	ds_read_b128 v[192:195], v160
	ds_read_b128 v[196:199], v160 offset:8192
	ds_read_b128 v[200:203], v161
	ds_read_b128 v[204:207], v161 offset:8192
	ds_read_b128 v[208:211], v162
	ds_read_b128 v[212:215], v162 offset:8192
	ds_read_b128 v[216:219], v163
	ds_read_b128 v[220:223], v163 offset:8192
	v_max3_f32 v250, v80, v81, v82
	v_max3_f32 v250, v250, v83, v84
	v_max3_f32 v250, v250, v85, v86
	v_max3_f32 v250, v250, v87, v88
	v_max3_f32 v250, v250, v89, v90
	v_max3_f32 v250, v250, v91, v92
	v_max3_f32 v250, v250, v93, v94
	v_max3_f32 v250, v250, v95, v64
	v_max3_f32 v250, v250, v65, v66
	v_max3_f32 v250, v250, v67, v68
	v_max3_f32 v250, v250, v69, v70
	v_max3_f32 v250, v250, v71, v72
	v_max3_f32 v250, v250, v73, v74
	v_max3_f32 v250, v250, v75, v76
	v_max3_f32 v250, v250, v77, v78
	v_max3_f32 v250, v250, v79, v79
	v_cmp_lt_f32_e64 vcc, s64, |v250|
	s_waitcnt vmcnt(0)
	ds_write_b128 v247, v[232:235]
	ds_write_b128 v247, v[236:239] offset:8192
	ds_write_b128 v183, v[240:243]
	ds_write_b128 v245, v[224:227]
	ds_write_b128 v245, v[228:231] offset:8192
	global_load_dwordx4 v[232:235], v180, s[50:51]
	global_load_dwordx4 v[236:239], v180, s[52:53]
	global_load_dwordx4 v[224:227], v180, s[54:55] offset:256
	global_load_dwordx4 v[228:231], v180, s[56:57] offset:256
	global_load_dwordx4 v[240:243], v181, s[58:59]
	s_cmp_lg_u32 s62, 0
	s_cbranch_scc1 .Lpp_safe_Bb
; __device__ __forceinline__ void partialSM(f32x16& p0, f32x16& p1, float& m_reg, float& mn, float& alpha) {
;     ...
;   for (int r = 0; r < 16; ++r) p0[r] = fmaf(p0[r], C, mnC); for (int r = 0; r < 16; ++r) p1[r] = fmaf(p1[r], C, mnC);
;   for (int r = 0; r < 16; ++r) p0[r] = __builtin_amdgcn_exp2f(p0[r]);
; }
; __device__ __forceinline__ void finishSM(f32x16& p0, f32x16& p1, float alpha, float& l_reg, bf16x8& pa0, bf16x8& pa1, bf16x8& pa2, bf16x8& pa3) {
;   for (int r = 0; r < 16; ++r) p1[r] = __builtin_amdgcn_exp2f(p1[r]);
;   float ps = 0; for (int r = 0; r < 16; ++r) ps += p0[r]; for (int r = 0; r < 16; ++r) ps += p1[r];
;   { auto rr = __builtin_amdgcn_permlane32_swap(__float_as_uint(ps), __float_as_uint(ps), false, false);
;     ps = __uint_as_float(rr[0]) + __uint_as_float(rr[1]); }
;   l_reg = l_reg * alpha + ps;
;     ...
;   PK4(p0, 0, pa0); PK4(p0, 8, pa1); PK4(p1, 0, pa2); PK4(p1, 8, pa3);
	s_cbranch_vccnz .Lpp_sw_Bb
	v_exp_f32_e32 v80, v80
	v_exp_f32_e32 v81, v81
	v_exp_f32_e32 v82, v82
	v_exp_f32_e32 v83, v83
	v_exp_f32_e32 v84, v84
	v_exp_f32_e32 v85, v85
	v_exp_f32_e32 v86, v86
	v_exp_f32_e32 v87, v87
	v_exp_f32_e32 v88, v88
	v_exp_f32_e32 v89, v89
	v_exp_f32_e32 v90, v90
	v_exp_f32_e32 v91, v91
	v_exp_f32_e32 v92, v92
	v_exp_f32_e32 v93, v93
	v_exp_f32_e32 v94, v94
	v_exp_f32_e32 v95, v95
	v_exp_f32_e32 v64, v64
	v_exp_f32_e32 v65, v65
	v_exp_f32_e32 v66, v66
	v_exp_f32_e32 v67, v67
	v_exp_f32_e32 v68, v68
	v_exp_f32_e32 v69, v69
	v_exp_f32_e32 v70, v70
	v_exp_f32_e32 v71, v71
	v_exp_f32_e32 v72, v72
	v_exp_f32_e32 v73, v73
	v_exp_f32_e32 v74, v74
	v_exp_f32_e32 v75, v75
	v_exp_f32_e32 v76, v76
	v_exp_f32_e32 v77, v77
	v_exp_f32_e32 v78, v78
	v_exp_f32_e32 v79, v79
	v_add_f32_e32 v249, v80, v81
	v_add_f32_e32 v250, v82, v83
	v_add_f32_e32 v251, v84, v85
	v_add_f32_e32 v182, v86, v87
	v_add_f32_e32 v249, v88, v249
	v_add_f32_e32 v250, v89, v250
	v_add_f32_e32 v251, v90, v251
	v_add_f32_e32 v182, v91, v182
	v_add_f32_e32 v249, v92, v249
	v_add_f32_e32 v250, v93, v250
	v_add_f32_e32 v251, v94, v251
	v_add_f32_e32 v182, v95, v182
	v_add_f32_e32 v249, v64, v249
	v_add_f32_e32 v250, v65, v250
	v_add_f32_e32 v251, v66, v251
	v_add_f32_e32 v182, v67, v182
	v_add_f32_e32 v249, v68, v249
	v_add_f32_e32 v250, v69, v250
	v_add_f32_e32 v251, v70, v251
	v_add_f32_e32 v182, v71, v182
	v_add_f32_e32 v249, v72, v249
	v_add_f32_e32 v250, v73, v250
	v_add_f32_e32 v251, v74, v251
	v_add_f32_e32 v182, v75, v182
	v_add_f32_e32 v249, v76, v249
	v_add_f32_e32 v250, v77, v250
	v_add_f32_e32 v251, v78, v251
	v_add_f32_e32 v182, v79, v182
	v_add_f32_e32 v249, v249, v250
	v_add_f32_e32 v251, v251, v182
	v_add_f32_e32 v249, v249, v251
	v_add_f32_e32 v176, v176, v249
	v_cvt_pk_bf16_f32 v144, v80, v81
	v_cvt_pk_bf16_f32 v145, v82, v83
	v_cvt_pk_bf16_f32 v146, v84, v85
	v_cvt_pk_bf16_f32 v147, v86, v87
	v_cvt_pk_bf16_f32 v148, v88, v89
	v_cvt_pk_bf16_f32 v149, v90, v91
	v_cvt_pk_bf16_f32 v150, v92, v93
	v_cvt_pk_bf16_f32 v151, v94, v95
	v_cvt_pk_bf16_f32 v152, v64, v65
	v_cvt_pk_bf16_f32 v153, v66, v67
	v_cvt_pk_bf16_f32 v154, v68, v69
	v_cvt_pk_bf16_f32 v155, v70, v71
	v_cvt_pk_bf16_f32 v156, v72, v73
	v_cvt_pk_bf16_f32 v157, v74, v75
	v_cvt_pk_bf16_f32 v158, v76, v77
	v_cvt_pk_bf16_f32 v159, v78, v79
; __device__ __forceinline__ void qkt(f32x16& p0, f32x16& p1, const char* Kn, const char* Kp, const bf16x8* qr, int r32, int hi) {
;   p0 = f32x16{}; p1 = f32x16{};
; #pragma unroll
;   for (int d0 = 0; d0 < 8; ++d0) { int cb = (d0 * 16 + hi * 8) * 2;
;     bf16x8 b0 = *reinterpret_cast<const bf16x8*>(Kn + KSWZ(r32, cb));
;     bf16x8 b1 = *reinterpret_cast<const bf16x8*>(Kn + KSWZ(32 + r32, cb));
;     p0 = __builtin_amdgcn_mfma_f32_32x32x16_bf16(b0, qr[d0], p0, 0, 0, 0);
;     p1 = __builtin_amdgcn_mfma_f32_32x32x16_bf16(b1, qr[d0], p1, 0, 0, 0); }
; #pragma unroll
;   for (int d1 = 0; d1 < 4; ++d1) { int cb = (d1 * 16 + hi * 8) * 2;
;     bf16x8 b0 = *reinterpret_cast<const bf16x8*>(Kp + KPSWZ(r32, cb));
;     bf16x8 b1 = *reinterpret_cast<const bf16x8*>(Kp + KPSWZ(32 + r32, cb));
;     p0 = __builtin_amdgcn_mfma_f32_32x32x16_bf16(b0, qr[8 + d1], p0, 0, 0, 0);
;     p1 = __builtin_amdgcn_mfma_f32_32x32x16_bf16(b1, qr[8 + d1], p1, 0, 0, 0); }
; }
; __device__ __forceinline__ int v_st(int k, int c) { const int kk = (k & ~0xC) | ((k & 4) << 1) | ((k & 8) >> 1); return ((kk >> 3) * 4 + (c >> 5)) * 512 + ((kk & 7) * 32 + (c & 31)) * 2; }
; __device__ __forceinline__ int v_rd_base(int lane) { return ((lane & 3) << 3) | (((lane >> 2) & 3) << 6) | (((lane >> 4) & 1) << 5) | (((lane >> 5) & 1) << 8); }
; template <int OFF> __device__ __forceinline__ s16x4 tr_read(int vb) {
;   s16x4 r; asm volatile("ds_read_b64_tr_b16 %0, %1 offset:%2" : "=&v"(r) : "v"(vb), "i"(OFF) : "memory"); return r;
; }
; template <int D0> __device__ __forceinline__ void pv_one(f32x16& od, int vb, bf16x8 pa0, bf16x8 pa1, bf16x8 pa2, bf16x8 pa3) {
;   const s16x4 l0 = tr_read<v_rd_off(D0, 0, 0)>(vb), h0 = tr_read<v_rd_off(D0, 0, 1)>(vb), l1 = tr_read<v_rd_off(D0, 1, 0)>(vb), h1 = tr_read<v_rd_off(D0, 1, 1)>(vb);
;   const s16x4 l2 = tr_read<v_rd_off(D0, 2, 0)>(vb), h2 = tr_read<v_rd_off(D0, 2, 1)>(vb), l3 = tr_read<v_rd_off(D0, 3, 0)>(vb), h3 = tr_read<v_rd_off(D0, 3, 1)>(vb);
;   asm volatile("s_waitcnt lgkmcnt(0)" ::: "memory"); SBAR();
;     ...
;   od = __builtin_amdgcn_mfma_f32_32x32x16_bf16(pa0, PK(l0, h0), od, 0, 0, 0);
;   od = __builtin_amdgcn_mfma_f32_32x32x16_bf16(pa1, PK(l1, h1), od, 0, 0, 0);
;   od = __builtin_amdgcn_mfma_f32_32x32x16_bf16(pa2, PK(l2, h2), od, 0, 0, 0);
;   od = __builtin_amdgcn_mfma_f32_32x32x16_bf16(pa3, PK(l3, h3), od, 0, 0, 0);
;     ...
; }
.Lpp_send_Bb:
	s_add_i32 s11, s11, 1
	s_cmp_eq_u32 s11, 68
	s_cbranch_scc1 .Lpp_last
	s_waitcnt lgkmcnt(6)
	v_mfma_f32_32x32x16_bf16 v[80:95], v[192:195], v[136:139], 0
	v_mfma_f32_32x32x16_bf16 v[64:79], v[196:199], v[136:139], 0
	s_add_i32 s36, s35, 2
	s_min_u32 s36, s36, 67
	s_lshl_b32 s44, s36, 6
	ds_read_b128 v[192:195], v164
	ds_read_b128 v[196:199], v164 offset:8192
	s_waitcnt lgkmcnt(6)
	v_mfma_f32_32x32x16_bf16 v[80:95], v[200:203], v[132:135], v[80:95]
	v_mfma_f32_32x32x16_bf16 v[64:79], v[204:207], v[132:135], v[64:79]
	s_add_i32 s45, s31, s44
	s_add_i32 s46, s24, s44
	s_add_i32 s46, s46, 0xffffff00
	ds_read_b128 v[200:203], v165
	ds_read_b128 v[204:207], v165 offset:8192
	s_waitcnt lgkmcnt(6)
	v_mfma_f32_32x32x16_bf16 v[80:95], v[208:211], v[128:131], v[80:95]
	v_mfma_f32_32x32x16_bf16 v[64:79], v[212:215], v[128:131], v[64:79]
	s_cmp_lt_u32 s36, 4
	s_cselect_b32 s36, s45, s46
	s_add_i32 s37, s35, 1
	ds_read_b128 v[208:211], v166
	ds_read_b128 v[212:215], v166 offset:8192
	s_waitcnt lgkmcnt(6)
	v_mfma_f32_32x32x16_bf16 v[80:95], v[216:219], v[124:127], v[80:95]
	v_mfma_f32_32x32x16_bf16 v[64:79], v[220:223], v[124:127], v[64:79]
	s_min_u32 s37, s37, 67
	s_lshl_b32 s44, s37, 6
	s_add_i32 s45, s31, s44
	ds_read_b128 v[216:219], v167
	ds_read_b128 v[220:223], v167 offset:8192
	s_waitcnt lgkmcnt(6)
	v_mfma_f32_32x32x16_bf16 v[80:95], v[192:195], v[120:123], v[80:95]
	v_mfma_f32_32x32x16_bf16 v[64:79], v[196:199], v[120:123], v[64:79]
	s_add_i32 s46, s24, s44
	s_add_i32 s46, s46, 0xffffff00
	s_cmp_lt_u32 s37, 4
	ds_read_b128 v[192:195], v168
	ds_read_b128 v[196:199], v168 offset:4096
	s_waitcnt lgkmcnt(6)
	v_mfma_f32_32x32x16_bf16 v[80:95], v[200:203], v[140:143], v[80:95]
	v_mfma_f32_32x32x16_bf16 v[64:79], v[204:207], v[140:143], v[64:79]
	s_cselect_b32 s37, s45, s46
	s_add_i32 s35, s35, 1
	s_lshl_b32 s44, s36, 12
	ds_read_b128 v[200:203], v169
	ds_read_b128 v[204:207], v169 offset:4096
	s_waitcnt lgkmcnt(6)
	v_mfma_f32_32x32x16_bf16 v[80:95], v[208:211], v[116:119], v[80:95]
	v_mfma_f32_32x32x16_bf16 v[64:79], v[212:215], v[116:119], v[64:79]
	s_add_u32 s50, s47, s44
	s_addc_u32 s51, s63, 0
	s_add_u32 s52, s50, 0x20000
	ds_read_b128 v[208:211], v170
	ds_read_b128 v[212:215], v170 offset:4096
	s_waitcnt lgkmcnt(6)
	v_mfma_f32_32x32x16_bf16 v[80:95], v[216:219], v[112:115], v[80:95]
	v_mfma_f32_32x32x16_bf16 v[64:79], v[220:223], v[112:115], v[64:79]
	s_addc_u32 s53, s51, 0
	s_lshl_b32 s44, s37, 12
	s_add_u32 s54, s47, s44
	ds_read_b128 v[216:219], v171
	ds_read_b128 v[220:223], v171 offset:4096
	s_waitcnt lgkmcnt(6)
	v_mfma_f32_32x32x16_bf16 v[80:95], v[192:195], v[108:111], v[80:95]
	v_mfma_f32_32x32x16_bf16 v[64:79], v[196:199], v[108:111], v[64:79]
	s_addc_u32 s55, s63, 0
	s_add_u32 s56, s54, 0x20000
	s_addc_u32 s57, s55, 0
	ds_read_b64_tr_b16 v[192:193], v174 offset:16384
	ds_read_b64_tr_b16 v[194:195], v174 offset:18432
	ds_read_b64_tr_b16 v[196:197], v174 offset:20480
	ds_read_b64_tr_b16 v[198:199], v174 offset:22528
	s_waitcnt lgkmcnt(8)
	v_mfma_f32_32x32x16_bf16 v[80:95], v[200:203], v[104:107], v[80:95]
	v_mfma_f32_32x32x16_bf16 v[64:79], v[204:207], v[104:107], v[64:79]
	s_lshl_b32 s44, s36, 10
	s_add_u32 s58, s60, s44
	s_addc_u32 s59, s61, 0
	ds_read_b64_tr_b16 v[200:201], v174 offset:24576
	ds_read_b64_tr_b16 v[202:203], v174 offset:26624
	ds_read_b64_tr_b16 v[204:205], v174 offset:28672
	ds_read_b64_tr_b16 v[206:207], v174 offset:30720
	s_waitcnt lgkmcnt(10)
	v_mfma_f32_32x32x16_bf16 v[80:95], v[208:211], v[100:103], v[80:95]
	v_mfma_f32_32x32x16_bf16 v[64:79], v[212:215], v[100:103], v[64:79]
	ds_read_b64_tr_b16 v[208:209], v174 offset:16896
	ds_read_b64_tr_b16 v[210:211], v174 offset:18944
	ds_read_b64_tr_b16 v[212:213], v174 offset:20992
	ds_read_b64_tr_b16 v[214:215], v174 offset:23040
	s_waitcnt lgkmcnt(12)
	v_mfma_f32_32x32x16_bf16 v[80:95], v[216:219], v[96:99], v[80:95]
	v_mfma_f32_32x32x16_bf16 v[64:79], v[220:223], v[96:99], v[64:79]
	ds_read_b64_tr_b16 v[216:217], v174 offset:25088
	ds_read_b64_tr_b16 v[218:219], v174 offset:27136
	ds_read_b64_tr_b16 v[220:221], v174 offset:29184
	ds_read_b64_tr_b16 v[222:223], v174 offset:31232
	s_waitcnt lgkmcnt(12)
	v_mfma_f32_32x32x16_bf16 v[0:15], v[144:147], v[192:195], v[0:15]
	ds_read_b64_tr_b16 v[192:193], v174 offset:17408
	ds_read_b64_tr_b16 v[194:195], v174 offset:19456
	v_mfma_f32_32x32x16_bf16 v[0:15], v[148:151], v[196:199], v[0:15]
	ds_read_b64_tr_b16 v[196:197], v174 offset:21504
	ds_read_b64_tr_b16 v[198:199], v174 offset:23552
	s_waitcnt lgkmcnt(12)
	v_mfma_f32_32x32x16_bf16 v[0:15], v[152:155], v[200:203], v[0:15]
	ds_read_b64_tr_b16 v[200:201], v174 offset:25600
	ds_read_b64_tr_b16 v[202:203], v174 offset:27648
	v_mfma_f32_32x32x16_bf16 v[0:15], v[156:159], v[204:207], v[0:15]
	ds_read_b64_tr_b16 v[204:205], v174 offset:29696
	ds_read_b64_tr_b16 v[206:207], v174 offset:31744
	s_waitcnt lgkmcnt(12)
	v_mfma_f32_32x32x16_bf16 v[48:63], v[144:147], v[208:211], v[48:63]
	ds_read_b64_tr_b16 v[208:209], v174 offset:17920
	ds_read_b64_tr_b16 v[210:211], v174 offset:19968
	v_mfma_f32_32x32x16_bf16 v[48:63], v[148:151], v[212:215], v[48:63]
	ds_read_b64_tr_b16 v[212:213], v174 offset:22016
	ds_read_b64_tr_b16 v[214:215], v174 offset:24064
	s_waitcnt lgkmcnt(12)
	v_mfma_f32_32x32x16_bf16 v[48:63], v[152:155], v[216:219], v[48:63]
	ds_read_b64_tr_b16 v[216:217], v174 offset:26112
	ds_read_b64_tr_b16 v[218:219], v174 offset:28160
	v_mfma_f32_32x32x16_bf16 v[48:63], v[156:159], v[220:223], v[48:63]
	ds_read_b64_tr_b16 v[220:221], v174 offset:30208
	ds_read_b64_tr_b16 v[222:223], v174 offset:32256
	s_waitcnt lgkmcnt(12)
	v_mfma_f32_32x32x16_bf16 v[32:47], v[144:147], v[192:195], v[32:47]
	v_mfma_f32_32x32x16_bf16 v[32:47], v[148:151], v[196:199], v[32:47]
	s_waitcnt lgkmcnt(8)
	v_mfma_f32_32x32x16_bf16 v[32:47], v[152:155], v[200:203], v[32:47]
	v_mfma_f32_32x32x16_bf16 v[32:47], v[156:159], v[204:207], v[32:47]
	s_waitcnt lgkmcnt(4)
	v_mfma_f32_32x32x16_bf16 v[16:31], v[144:147], v[208:211], v[16:31]
	v_mfma_f32_32x32x16_bf16 v[16:31], v[148:151], v[212:215], v[16:31]
	s_waitcnt lgkmcnt(0)
	v_mfma_f32_32x32x16_bf16 v[16:31], v[152:155], v[216:219], v[16:31]
	v_mfma_f32_32x32x16_bf16 v[16:31], v[156:159], v[220:223], v[16:31]
	s_branch .Lpp_loop

; __device__ __forceinline__ void partialSM(f32x16& p0, f32x16& p1, float& m_reg, float& mn, float& alpha) {
;   constexpr float C = SCALE * 1.4426950408889634f;
;   float pmax = p0[0]; for (int r = 1; r < 16; ++r) pmax = fmaxf(pmax, p0[r]); for (int r = 0; r < 16; ++r) pmax = fmaxf(pmax, p1[r]);
;   { auto rr = __builtin_amdgcn_permlane32_swap(__float_as_uint(pmax), __float_as_uint(pmax), false, false);
;     pmax = fmaxf(__uint_as_float(rr[0]), __uint_as_float(rr[1])); }
;   if (__builtin_expect(__all(pmax - m_reg <= THR / SCALE), 1)) { mn = m_reg; alpha = 1.f; }
;   else { mn = fmaxf(m_reg, pmax); alpha = __builtin_amdgcn_exp2f((m_reg - mn) * C); m_reg = mn; }
.Lpp_safe_Ba:
	v_mov_b32_e32 v251, v250
	s_nop 1
	v_permlane32_swap_b32_e32 v250, v251
	v_max_f32_e32 v250, v250, v251
	v_sub_f32_e32 v251, v250, v175
	v_cmp_ge_f32_e32 vcc, 0x4138aa3b, v251
	v_max_f32_e32 v249, v175, v250
	v_sub_f32_e32 v251, v175, v249
	v_exp_f32_e32 v251, v251
	s_nop 1
	s_cmp_eq_u64 vcc, exec
	s_cselect_b64 s[8:9], -1, 0
	v_cndmask_b32_e64 v177, v251, 1.0, s[8:9]
	v_cndmask_b32_e64 v175, v249, v175, s[8:9]
	v_cmp_gt_f32_e32 vcc, 1.0, v177
	s_nop 4
	s_cbranch_vccz .Lpp_nr_Ba
	s_and_saveexec_b64 s[42:43], s[6:7]
	ds_write_b32 v186, v177 offset:128
	s_or_b64 exec, exec, s[42:43]
	s_waitcnt lgkmcnt(0)
	v_add_u32_e32 v187, v179, v172
	ds_read_b128 v[192:195], v187 offset:128
	ds_read_b128 v[196:199], v187 offset:160
	ds_read_b128 v[200:203], v187 offset:192
	ds_read_b128 v[204:207], v187 offset:224
	s_waitcnt lgkmcnt(0)
	v_pk_mul_f32 v[0:1], v[0:1], v[192:193]
	v_pk_mul_f32 v[2:3], v[2:3], v[194:195]
	v_pk_mul_f32 v[4:5], v[4:5], v[196:197]
	v_pk_mul_f32 v[6:7], v[6:7], v[198:199]
	v_pk_mul_f32 v[8:9], v[8:9], v[200:201]
	v_pk_mul_f32 v[10:11], v[10:11], v[202:203]
	v_pk_mul_f32 v[12:13], v[12:13], v[204:205]
	v_pk_mul_f32 v[14:15], v[14:15], v[206:207]
	v_pk_mul_f32 v[48:49], v[48:49], v[192:193]
	v_pk_mul_f32 v[50:51], v[50:51], v[194:195]
	v_pk_mul_f32 v[52:53], v[52:53], v[196:197]
	v_pk_mul_f32 v[54:55], v[54:55], v[198:199]
	v_pk_mul_f32 v[56:57], v[56:57], v[200:201]
	v_pk_mul_f32 v[58:59], v[58:59], v[202:203]
	v_pk_mul_f32 v[60:61], v[60:61], v[204:205]
	v_pk_mul_f32 v[62:63], v[62:63], v[206:207]
	v_pk_mul_f32 v[32:33], v[32:33], v[192:193]
	v_pk_mul_f32 v[34:35], v[34:35], v[194:195]
	v_pk_mul_f32 v[36:37], v[36:37], v[196:197]
	v_pk_mul_f32 v[38:39], v[38:39], v[198:199]
	v_pk_mul_f32 v[40:41], v[40:41], v[200:201]
	v_pk_mul_f32 v[42:43], v[42:43], v[202:203]
	v_pk_mul_f32 v[44:45], v[44:45], v[204:205]
	v_pk_mul_f32 v[46:47], v[46:47], v[206:207]
	v_pk_mul_f32 v[16:17], v[16:17], v[192:193]
	v_pk_mul_f32 v[18:19], v[18:19], v[194:195]
	v_pk_mul_f32 v[20:21], v[20:21], v[196:197]
	v_pk_mul_f32 v[22:23], v[22:23], v[198:199]
	v_pk_mul_f32 v[24:25], v[24:25], v[200:201]
	v_pk_mul_f32 v[26:27], v[26:27], v[202:203]
	v_pk_mul_f32 v[28:29], v[28:29], v[204:205]
	v_pk_mul_f32 v[30:31], v[30:31], v[206:207]
	s_nop 1
	ds_read_b128 v[192:195], v160 offset:16384
	ds_read_b128 v[196:199], v160 offset:24576
	ds_read_b128 v[200:203], v161 offset:16384
	ds_read_b128 v[204:207], v161 offset:24576
	s_waitcnt lgkmcnt(0)

; __device__ __forceinline__ void partialSM(f32x16& p0, f32x16& p1, float& m_reg, float& mn, float& alpha) {
;   constexpr float C = SCALE * 1.4426950408889634f;
;   float pmax = p0[0]; for (int r = 1; r < 16; ++r) pmax = fmaxf(pmax, p0[r]); for (int r = 0; r < 16; ++r) pmax = fmaxf(pmax, p1[r]);
;   { auto rr = __builtin_amdgcn_permlane32_swap(__float_as_uint(pmax), __float_as_uint(pmax), false, false);
;     pmax = fmaxf(__uint_as_float(rr[0]), __uint_as_float(rr[1])); }
;   if (__builtin_expect(__all(pmax - m_reg <= THR / SCALE), 1)) { mn = m_reg; alpha = 1.f; }
;   else { mn = fmaxf(m_reg, pmax); alpha = __builtin_amdgcn_exp2f((m_reg - mn) * C); m_reg = mn; }
.Lpp_safe_Bb:
	v_mov_b32_e32 v251, v250
	s_nop 1
	v_permlane32_swap_b32_e32 v250, v251
	v_max_f32_e32 v250, v250, v251
	v_sub_f32_e32 v251, v250, v175
	v_cmp_ge_f32_e32 vcc, 0x4138aa3b, v251
	v_max_f32_e32 v249, v175, v250
	v_sub_f32_e32 v251, v175, v249
	v_exp_f32_e32 v251, v251
	s_nop 1
	s_cmp_eq_u64 vcc, exec
	s_cselect_b64 s[8:9], -1, 0
	v_cndmask_b32_e64 v177, v251, 1.0, s[8:9]
	v_cndmask_b32_e64 v175, v249, v175, s[8:9]
	v_cmp_gt_f32_e32 vcc, 1.0, v177
	s_nop 4
	s_cbranch_vccz .Lpp_nr_Bb
	s_and_saveexec_b64 s[42:43], s[6:7]
	ds_write_b32 v186, v177 offset:128
	s_or_b64 exec, exec, s[42:43]
	s_waitcnt lgkmcnt(0)
	v_add_u32_e32 v187, v179, v172
	ds_read_b128 v[192:195], v187 offset:128
	ds_read_b128 v[196:199], v187 offset:160
	ds_read_b128 v[200:203], v187 offset:192
	ds_read_b128 v[204:207], v187 offset:224
	s_waitcnt lgkmcnt(0)
	v_pk_mul_f32 v[0:1], v[0:1], v[192:193]
	v_pk_mul_f32 v[2:3], v[2:3], v[194:195]
	v_pk_mul_f32 v[4:5], v[4:5], v[196:197]
	v_pk_mul_f32 v[6:7], v[6:7], v[198:199]
	v_pk_mul_f32 v[8:9], v[8:9], v[200:201]
	v_pk_mul_f32 v[10:11], v[10:11], v[202:203]
	v_pk_mul_f32 v[12:13], v[12:13], v[204:205]
	v_pk_mul_f32 v[14:15], v[14:15], v[206:207]
	v_pk_mul_f32 v[48:49], v[48:49], v[192:193]
	v_pk_mul_f32 v[50:51], v[50:51], v[194:195]
	v_pk_mul_f32 v[52:53], v[52:53], v[196:197]
	v_pk_mul_f32 v[54:55], v[54:55], v[198:199]
	v_pk_mul_f32 v[56:57], v[56:57], v[200:201]
	v_pk_mul_f32 v[58:59], v[58:59], v[202:203]
	v_pk_mul_f32 v[60:61], v[60:61], v[204:205]
	v_pk_mul_f32 v[62:63], v[62:63], v[206:207]
	v_pk_mul_f32 v[32:33], v[32:33], v[192:193]
	v_pk_mul_f32 v[34:35], v[34:35], v[194:195]
	v_pk_mul_f32 v[36:37], v[36:37], v[196:197]
	v_pk_mul_f32 v[38:39], v[38:39], v[198:199]
	v_pk_mul_f32 v[40:41], v[40:41], v[200:201]
	v_pk_mul_f32 v[42:43], v[42:43], v[202:203]
	v_pk_mul_f32 v[44:45], v[44:45], v[204:205]
	v_pk_mul_f32 v[46:47], v[46:47], v[206:207]
	v_pk_mul_f32 v[16:17], v[16:17], v[192:193]
	v_pk_mul_f32 v[18:19], v[18:19], v[194:195]
	v_pk_mul_f32 v[20:21], v[20:21], v[196:197]
	v_pk_mul_f32 v[22:23], v[22:23], v[198:199]
	v_pk_mul_f32 v[24:25], v[24:25], v[200:201]
	v_pk_mul_f32 v[26:27], v[26:27], v[202:203]
	v_pk_mul_f32 v[28:29], v[28:29], v[204:205]
	v_pk_mul_f32 v[30:31], v[30:31], v[206:207]
	s_nop 1
	ds_read_b128 v[192:195], v160
	ds_read_b128 v[196:199], v160 offset:8192
	ds_read_b128 v[200:203], v161
	ds_read_b128 v[204:207], v161 offset:8192
	s_waitcnt lgkmcnt(0)
